# attention loop bodies re-scheduled (MFMA/VALU interleave, v_add row sums), attention+DFT phase rebalanced 3/5 units, weight conversion moved to DFT CUs
# speedup vs baseline: 1.0258x; 1.0258x over previous
; DI void phase_att(const Frame& F) {
;     const bool lastl = (F.l == NL - 1);
;     const int nun = (!lastl && F.vcu < 128) ? 5 : 4;
; #pragma unroll 1
;     for (int i = 0; i < nun; ++i) {
;         int kind, b, h, q0, nt;
;         if (i < 4) { const int idx = (i >> 1) * 256 + F.vcu; kind = i & 1; b = idx >> 6; h = (idx >> 3) & 7; q0 = b * SEQ + (idx & 7) * 256; nt = 36; }
;         else { const int idx = F.vcu >> 1; kind = F.vcu & 1; b = idx >> 3; h = idx & 7; q0 = ML + b * CTXL; nt = 4; }
.LBB0_352:
	s_and_b64 vcc, exec, s[2:3]
	s_cbranch_vccz .LBB0_506
	v_writelane_b32 v255, s81, 45
	s_add_i32 s2, s70, 0xffe5
	v_writelane_b32 v255, s70, 46
	s_and_b32 s2, s2, 0xff
	s_cmp_gt_u32 s2, 8
	v_readlane_b32 s4, v255, 29
	s_cselect_b64 s[6:7], -1, 0
	s_cmpk_lt_u32 s4, 0x80
	s_cselect_b64 s[2:3], -1, 0
	v_writelane_b32 v255, s6, 42
	s_and_b64 s[2:3], s[6:7], s[2:3]
	s_and_b64 s[2:3], s[2:3], exec
	s_cselect_b32 s10, 5, 4
	s_lshr_b32 s2, s4, 4
	s_lshl_b32 s34, s2, 8
	s_lshl_b32 s3, s4, 8
	s_lshr_b32 s11, s4, 1
	s_add_i32 s35, s34, 0x4000
	s_lshr_b32 s41, s4, 3
	s_and_b32 s3, s3, 0x700
	s_add_u32 s55, s94, 0x7880000
	s_addc_u32 s56, s95, 0
	s_add_u32 s57, s94, 0x7d00000
	s_addc_u32 s58, s95, 0
	s_add_u32 s59, s94, 0x7400000
	s_addc_u32 s60, s95, 0
	s_add_u32 s61, s94, 0xa300000
	s_addc_u32 s62, s95, 0
	s_add_u32 s63, s94, 0xb500000
	s_addc_u32 s70, s95, 0
	s_add_u32 s71, s94, 0x9100000
	s_addc_u32 s40, s95, 0
	s_add_u32 s12, s94, 0x8f00000
	v_writelane_b32 v255, s7, 43
	s_addc_u32 s13, s95, 0
	v_writelane_b32 v255, s3, 40
	s_add_u32 s6, s94, 0xe200000
	s_addc_u32 s7, s95, 0
	s_lshl_b32 s97, s2, 11
	v_readlane_b32 s2, v255, 8
	s_add_u32 s14, s2, s44
	v_readlane_b32 s2, v255, 9
	s_addc_u32 s15, s2, s45
	v_readlane_b32 s4, v255, 29
	s_bfe_u32 s100, s4, 0x10004
	s_cmp_eq_u32 s100, 0
	s_cbranch_scc1 .Latt_nond
	s_lshr_b32 s2, s4, 5
	s_lshl_b32 s2, s2, 4
	s_and_b32 s3, s4, 15
	s_or_b32 s2, s2, s3
	s_lshr_b32 s11, s2, 1
	s_lshr_b32 s2, s2, 4
	s_lshl_b32 s34, s2, 8
	s_add_i32 s35, s34, 0x4000
	s_lshl_b32 s97, s2, 11
	v_readlane_b32 s2, v255, 42
	s_and_b32 s2, s2, 1
	s_add_i32 s10, s2, 3
	s_branch .Latt_go
.Latt_nond:
	s_mov_b32 s10, 5
.Latt_go:
	s_mov_b32 s38, 0
	s_branch .LBB0_357

; DI void phase_att(const Frame& F) {
;     ...
;     for (int i = 0; i < nun; ++i) {
;         int kind, b, h, q0, nt;
;         if (i < 4) { const int idx = (i >> 1) * 256 + F.vcu; kind = i & 1; b = idx >> 6; h = (idx >> 3) & 7; q0 = b * SEQ + (idx & 7) * 256; nt = 36; }
;         else { const int idx = F.vcu >> 1; kind = F.vcu & 1; b = idx >> 3; h = idx & 7; q0 = ML + b * CTXL; nt = 4; }
;         if (kind == 0) attn_unit<0>(F, q0, h, ML + b * CTXL, b * SEQ, nt);
;         else attn_unit<1>(F, q0, h, ML + b * CTXL, b * SEQ, nt);
.LBB0_357:
	s_mov_b32 s54, 4
	s_mov_b32 s36, s97
	s_mov_b32 s81, s35
	s_mov_b32 s39, s34
	s_mov_b32 s8, s35
	s_mov_b32 s65, s11
	v_readlane_b32 s2, v255, 29
	s_cmp_eq_u32 s100, 0
	s_cselect_b32 s3, 99, 3
	s_cmp_eq_u32 s38, s3
	s_cbranch_scc1 .LBB0_359
	s_min_u32 s101, s38, 3
	s_cmp_eq_u32 s38, 4
	s_cselect_b32 s3, 16, 0
	v_readlane_b32 s65, v255, 29
	s_add_i32 s65, s65, s3
	s_lshl_b32 s2, s101, 7
	s_and_b32 s2, s2, 0x100
	s_add_i32 s2, s2, s65
	s_lshr_b32 s2, s2, 6
	s_lshl_b32 s36, s2, 11
	v_readlane_b32 s3, v255, 40
	s_lshl_b32 s39, s2, 8
	s_or_b32 s8, s36, s3
	s_or_b32 s81, s39, 0x4000
	s_mov_b32 s54, 36
	s_lshr_b32 s65, s65, 3
	s_mov_b32 s2, s101

; template <int KIND>
; DI void attn_unit(const Frame& F, int qrow0, int head, int ctx_row0, int lat_row0, int ntiles) {
;     ...
;     bf16x8 pfa[2][2], pfb[2][2];
;     f32x16 s0, s1, n0, n1;
.LBB0_365:
	s_cmp_lt_u32 s28, 3
	s_cselect_b32 s2, s43, s23
	v_add_u32_e32 v64, s2, v165
	v_ashrrev_i32_e32 v65, 31, v64
	v_lshlrev_b64 v[64:65], 8, v[64:65]
	v_lshl_add_u64 v[64:65], v[150:151], 0, v[64:65]
	global_load_dwordx4 v[118:121], v[64:65], off
	s_add_i32 s2, s27, 0xffffe000
	s_cmp_lg_u32 s27, 0
	s_cselect_b32 s2, s2, 0x4000
	v_add_u32_e32 v154, s2, v164
	ds_read_b64_tr_b16 v[234:235], v154 offset:28672
	ds_read_b64_tr_b16 v[236:237], v154 offset:29184
	ds_read_b64_tr_b16 v[238:239], v154 offset:32768
	ds_read_b64_tr_b16 v[240:241], v154 offset:33280
	ds_read_b64_tr_b16 v[242:243], v154 offset:29696
	ds_read_b64_tr_b16 v[244:245], v154 offset:30208
	ds_read_b64_tr_b16 v[246:247], v154 offset:33792
	ds_read_b64_tr_b16 v[248:249], v154 offset:34304
	ds_read_b128 v[138:141], v159
	ds_read_b128 v[142:145], v159 offset:32
	ds_read_b128 v[166:169], v159 offset:64
	ds_read_b128 v[170:173], v159 offset:96
	v_xor_b32_e32 v64, 0x80000000, v162
	v_mov_b32_e32 v65, v64
	v_mov_b64_e32 v[66:67], v[64:65]
	v_mov_b64_e32 v[68:69], v[64:65]
	v_mov_b64_e32 v[70:71], v[64:65]
	v_mov_b64_e32 v[72:73], v[64:65]
	v_mov_b64_e32 v[74:75], v[64:65]
	v_mov_b64_e32 v[76:77], v[64:65]
	v_mov_b64_e32 v[78:79], v[64:65]
	v_exp_f32_e32 v36, v36
	v_exp_f32_e32 v37, v37
	s_waitcnt lgkmcnt(10)
	v_mfma_f32_32x32x16_bf16 v[0:15], v[234:237], v[130:133], v[0:15]
	ds_read_b64_tr_b16 v[192:193], v154 offset:34816
	ds_read_b64_tr_b16 v[194:195], v154 offset:35328
	ds_read_b64_tr_b16 v[196:197], v154 offset:35840
	ds_read_b64_tr_b16 v[198:199], v154 offset:36352
	s_waitcnt lgkmcnt(12)
	v_mfma_f32_32x32x16_bf16 v[16:31], v[238:241], v[130:133], v[16:31]
	v_exp_f32_e32 v130, v48
	v_exp_f32_e32 v48, v32
	v_exp_f32_e32 v131, v49
	v_exp_f32_e32 v49, v33
	s_waitcnt lgkmcnt(10)
	v_mfma_f32_32x32x16_bf16 v[0:15], v[242:245], v[134:137], v[0:15]
	v_exp_f32_e32 v132, v50
	v_exp_f32_e32 v50, v34
	v_exp_f32_e32 v133, v51
	v_exp_f32_e32 v51, v35
	s_waitcnt lgkmcnt(8)
	v_mfma_f32_32x32x16_bf16 v[16:31], v[246:249], v[134:137], v[16:31]
	v_exp_f32_e32 v34, v42
	v_exp_f32_e32 v35, v43
	v_exp_f32_e32 v42, v46
	v_exp_f32_e32 v43, v47
	s_waitcnt lgkmcnt(7)
	v_mfma_f32_32x32x16_bf16 v[80:95], v[138:141], v[98:101], v[64:79]
	ds_read_b128 v[138:141], v159 offset:4640
	v_exp_f32_e32 v134, v52
	v_exp_f32_e32 v135, v53
	v_exp_f32_e32 v136, v54
	v_exp_f32_e32 v137, v55
	s_waitcnt lgkmcnt(7)
	v_mfma_f32_32x32x16_bf16 v[80:95], v[142:145], v[102:105], v[80:95]
	ds_read_b128 v[142:145], v159 offset:4672
	v_exp_f32_e32 v54, v58
	v_exp_f32_e32 v55, v59
	v_exp_f32_e32 v52, v38
	v_exp_f32_e32 v53, v39
	s_waitcnt lgkmcnt(7)
	v_mfma_f32_32x32x16_bf16 v[80:95], v[166:169], v[106:109], v[80:95]
	ds_read_b128 v[166:169], v159 offset:4704
	v_exp_f32_e32 v38, v56
	v_exp_f32_e32 v32, v40
	v_exp_f32_e32 v39, v57
	v_exp_f32_e32 v33, v41
	s_waitcnt lgkmcnt(7)
	v_mfma_f32_32x32x16_bf16 v[80:95], v[170:173], v[110:113], v[80:95]
	ds_read_b128 v[170:173], v159 offset:4608
	v_exp_f32_e32 v56, v60
	v_exp_f32_e32 v40, v44
	v_exp_f32_e32 v57, v61
	v_exp_f32_e32 v41, v45
	s_waitcnt lgkmcnt(3)
	v_mfma_f32_32x32x16_bf16 v[64:79], v[138:141], v[102:105], v[64:79]
	ds_read_b64_tr_b16 v[138:139], v154 offset:31744
	ds_read_b64_tr_b16 v[140:141], v154 offset:32256
	v_exp_f32_e32 v44, v62
	v_exp_f32_e32 v45, v63
	v_add_f32_e32 v46, v36, v37
	v_add_f32_e32 v47, v130, v48
	v_add_f32_e32 v46, v131, v46
	s_waitcnt lgkmcnt(4)
	v_mfma_f32_32x32x16_bf16 v[64:79], v[142:145], v[106:109], v[64:79]
	ds_read_b64_tr_b16 v[142:143], v154 offset:30720
	ds_read_b64_tr_b16 v[144:145], v154 offset:31232
	v_add_f32_e32 v47, v49, v47
	v_add_f32_e32 v46, v132, v46
	v_add_f32_e32 v47, v50, v47
	v_add_f32_e32 v46, v133, v46
	v_add_f32_e32 v47, v51, v47
	v_add_f32_e32 v46, v34, v46
	v_add_f32_e32 v47, v35, v47
	s_waitcnt lgkmcnt(5)
	v_mfma_f32_32x32x16_bf16 v[64:79], v[166:169], v[110:113], v[64:79]
	v_add_f32_e32 v46, v42, v46
	v_add_f32_e32 v47, v43, v47
	v_add_f32_e32 v46, v134, v46
	v_add_f32_e32 v47, v135, v47
	v_add_f32_e32 v46, v136, v46
	v_add_f32_e32 v47, v137, v47
	v_add_f32_e32 v46, v54, v46
	s_waitcnt lgkmcnt(4)
	v_mfma_f32_32x32x16_bf16 v[64:79], v[170:173], v[98:101], v[64:79]
	v_add_f32_e32 v47, v55, v47
	v_add_f32_e32 v46, v52, v46
	v_add_f32_e32 v47, v53, v47
	v_add_f32_e32 v46, v38, v46
	v_add_f32_e32 v47, v32, v47
	v_add_f32_e32 v46, v39, v46
	v_add_f32_e32 v47, v33, v47
	v_mfma_f32_32x32x16_bf16 v[16:31], v[192:195], v[126:129], v[16:31]
	v_add_f32_e32 v46, v56, v46
	v_add_f32_e32 v47, v40, v47
	v_add_f32_e32 v46, v57, v46
	v_add_f32_e32 v47, v41, v47
	v_add_f32_e32 v46, v44, v46
	v_add_f32_e32 v47, v45, v47
	v_add_f32_e32 v46, v46, v47
	v_mfma_f32_32x32x16_bf16 v[16:31], v[196:199], v[122:125], v[16:31]
	s_waitcnt lgkmcnt(2)
	v_mfma_f32_32x32x16_bf16 v[0:15], v[138:141], v[122:125], v[0:15]
	s_waitcnt lgkmcnt(0)
	v_mfma_f32_32x32x16_bf16 v[0:15], v[142:145], v[126:129], v[0:15]
	v_cmp_lt_f32_e32 vcc, s1, v46
	v_mov_b32_e32 v154, v46
	s_cbranch_vccnz .LBB0_381
	v_cvt_pk_bf16_f32 v130, v130, v131
	v_cvt_pk_bf16_f32 v131, v132, v133
	v_cvt_pk_bf16_f32 v132, v134, v135
	v_cvt_pk_bf16_f32 v133, v136, v137
	v_cvt_pk_bf16_f32 v122, v48, v49
	v_cvt_pk_bf16_f32 v123, v50, v51
	v_cvt_pk_bf16_f32 v124, v36, v37
	v_cvt_pk_bf16_f32 v125, v52, v53
	v_cvt_pk_bf16_f32 v134, v38, v39
	v_cvt_pk_bf16_f32 v135, v54, v55
	v_cvt_pk_bf16_f32 v136, v56, v57
	v_cvt_pk_bf16_f32 v137, v44, v45
	v_cvt_pk_bf16_f32 v126, v32, v33
	v_cvt_pk_bf16_f32 v127, v34, v35
	v_cvt_pk_bf16_f32 v128, v40, v41
	v_cvt_pk_bf16_f32 v129, v42, v43
	v_cndmask_b32_e64 v32, 0, 1, s[20:21]
	v_cmp_ne_u32_e64 s[2:3], 1, v32
	s_andn2_b64 vcc, exec, s[20:21]
	s_cbranch_vccnz .LBB0_368

; template <int KIND>
; DI void attn_unit(const Frame& F, int qrow0, int head, int ctx_row0, int lat_row0, int ntiles) {
;     ...
;     bf16x8 pfa[2][2], pfb[2][2];
;     f32x16 s0, s1, n0, n1;
.LBB0_372:
	s_add_i32 s2, s27, 0xffffe000
	s_cmp_lg_u32 s27, 0
	s_cselect_b32 s2, s2, 0x4000
	ds_read_b128 v[138:141], v159 offset:14336
	ds_read_b128 v[166:169], v159 offset:14368
	ds_read_b128 v[170:173], v159 offset:14400
	ds_read_b128 v[174:177], v159 offset:14432
	v_xor_b32_e32 v32, 0x80000000, v162
	v_mov_b32_e32 v33, v32
	v_mov_b64_e32 v[34:35], v[32:33]
	v_mov_b64_e32 v[36:37], v[32:33]
	v_mov_b64_e32 v[38:39], v[32:33]
	v_mov_b64_e32 v[40:41], v[32:33]
	v_mov_b64_e32 v[42:43], v[32:33]
	v_mov_b64_e32 v[44:45], v[32:33]
	v_mov_b64_e32 v[46:47], v[32:33]
	v_add_f32_e64 v142, v154, v155
	v_add_f32_e64 v143, v155, v154
	v_add_u32_e32 v143, s2, v164
	ds_read_b64_tr_b16 v[234:235], v143 offset:29696
	ds_read_b64_tr_b16 v[236:237], v143 offset:30208
	ds_read_b64_tr_b16 v[238:239], v143 offset:33792
	ds_read_b64_tr_b16 v[240:241], v143 offset:34304
	ds_read_b64_tr_b16 v[192:193], v143 offset:30720
	ds_read_b64_tr_b16 v[194:195], v143 offset:31232
	ds_read_b64_tr_b16 v[196:197], v143 offset:34816
	ds_read_b64_tr_b16 v[198:199], v143 offset:35328
	v_exp_f32_e32 v80, v80
	v_exp_f32_e32 v64, v64
	v_exp_f32_e32 v81, v81
	v_exp_f32_e32 v65, v65
	v_exp_f32_e32 v82, v82
	v_exp_f32_e32 v66, v66
	ds_read_b64_tr_b16 v[200:201], v143 offset:35840
	ds_read_b64_tr_b16 v[202:203], v143 offset:36352
	s_waitcnt lgkmcnt(13)
	v_mfma_f32_32x32x16_bf16 v[48:63], v[138:141], v[98:101], v[32:47]
	ds_read_b128 v[138:141], v159 offset:18976
	v_exp_f32_e32 v83, v83
	v_exp_f32_e32 v67, v67
	v_exp_f32_e32 v84, v84
	v_exp_f32_e32 v68, v68
	s_waitcnt lgkmcnt(13)
	v_mfma_f32_32x32x16_bf16 v[48:63], v[166:169], v[102:105], v[48:63]
	ds_read_b128 v[166:169], v159 offset:19008
	v_exp_f32_e32 v85, v85
	v_exp_f32_e32 v69, v69
	v_exp_f32_e32 v70, v70
	v_exp_f32_e32 v71, v71
	s_waitcnt lgkmcnt(10)
	v_mfma_f32_32x32x16_bf16 v[0:15], v[234:237], v[134:137], v[0:15]
	v_exp_f32_e32 v72, v72
	v_exp_f32_e32 v73, v73
	v_exp_f32_e32 v74, v74
	v_exp_f32_e32 v75, v75
	s_waitcnt lgkmcnt(8)
	v_mfma_f32_32x32x16_bf16 v[16:31], v[238:241], v[134:137], v[16:31]
	v_exp_f32_e32 v76, v76
	v_exp_f32_e32 v77, v77
	v_exp_f32_e32 v78, v78
	v_exp_f32_e32 v79, v79
	v_mfma_f32_32x32x16_bf16 v[48:63], v[170:173], v[106:109], v[48:63]
	ds_read_b128 v[170:173], v159 offset:19040
	v_exp_f32_e32 v134, v86
	v_exp_f32_e32 v135, v87
	v_exp_f32_e32 v86, v88
	v_exp_f32_e32 v87, v89
	v_mfma_f32_32x32x16_bf16 v[48:63], v[174:177], v[110:113], v[48:63]
	ds_read_b128 v[174:177], v159 offset:18944
	v_exp_f32_e32 v88, v90
	v_exp_f32_e32 v89, v91
	v_exp_f32_e32 v90, v92
	v_exp_f32_e32 v91, v93
	s_waitcnt lgkmcnt(3)
	v_mfma_f32_32x32x16_bf16 v[32:47], v[138:141], v[102:105], v[32:47]
	ds_read_b64_tr_b16 v[138:139], v143 offset:31744
	ds_read_b64_tr_b16 v[140:141], v143 offset:32256
	v_exp_f32_e32 v92, v94
	v_exp_f32_e32 v93, v95
	v_add_f32_e32 v94, v80, v64
	v_add_f32_e32 v95, v81, v65
	v_add_f32_e32 v94, v82, v94
	s_waitcnt lgkmcnt(4)
	v_mfma_f32_32x32x16_bf16 v[32:47], v[166:169], v[106:109], v[32:47]
	ds_read_b64_tr_b16 v[166:167], v143 offset:28672
	ds_read_b64_tr_b16 v[168:169], v143 offset:29184
	v_add_f32_e32 v95, v66, v95
	v_add_f32_e32 v94, v83, v94
	v_add_f32_e32 v95, v67, v95
	v_add_f32_e32 v94, v84, v94
	v_add_f32_e32 v95, v68, v95
	v_add_f32_e32 v94, v85, v94
	v_add_f32_e32 v95, v69, v95
	s_waitcnt lgkmcnt(5)
	v_mfma_f32_32x32x16_bf16 v[32:47], v[170:173], v[110:113], v[32:47]
	ds_read_b64_tr_b16 v[170:171], v143 offset:32768
	ds_read_b64_tr_b16 v[172:173], v143 offset:33280
	v_add_f32_e32 v94, v70, v94
	v_add_f32_e32 v95, v71, v95
	v_add_f32_e32 v94, v72, v94
	v_add_f32_e32 v95, v73, v95
	v_add_f32_e32 v94, v74, v94
	v_add_f32_e32 v95, v75, v95
	v_add_f32_e32 v94, v76, v94
	s_waitcnt lgkmcnt(6)
	v_mfma_f32_32x32x16_bf16 v[32:47], v[174:177], v[98:101], v[32:47]
	v_add_f32_e32 v95, v77, v95
	v_add_f32_e32 v94, v78, v94
	v_add_f32_e32 v95, v79, v95
	v_add_f32_e32 v94, v134, v94
	v_add_f32_e32 v95, v135, v95
	v_add_f32_e32 v94, v86, v94
	v_add_f32_e32 v95, v87, v95
	v_mfma_f32_32x32x16_bf16 v[0:15], v[192:195], v[122:125], v[0:15]
	v_add_f32_e32 v94, v88, v94
	v_add_f32_e32 v95, v89, v95
	v_add_f32_e32 v94, v90, v94
	v_add_f32_e32 v95, v91, v95
	v_add_f32_e32 v94, v92, v94
	v_add_f32_e32 v95, v93, v95
	v_add_f32_e32 v94, v94, v95
	v_mfma_f32_32x32x16_bf16 v[16:31], v[196:199], v[122:125], v[16:31]
	v_mfma_f32_32x32x16_bf16 v[16:31], v[200:203], v[126:129], v[16:31]
	s_waitcnt lgkmcnt(4)
	v_mfma_f32_32x32x16_bf16 v[0:15], v[138:141], v[126:129], v[0:15]
	s_waitcnt lgkmcnt(2)
	v_mfma_f32_32x32x16_bf16 v[0:15], v[166:169], v[130:133], v[0:15]
	s_waitcnt lgkmcnt(0)
	v_mfma_f32_32x32x16_bf16 v[16:31], v[170:173], v[130:133], v[16:31]
	v_cmp_lt_f32_e32 vcc, s1, v94
	s_cbranch_vccnz .LBB0_382
	v_cvt_pk_bf16_f32 v130, v80, v81
	v_cvt_pk_bf16_f32 v131, v82, v83
	v_cvt_pk_bf16_f32 v132, v84, v85
	v_cvt_pk_bf16_f32 v133, v134, v135
	v_cvt_pk_bf16_f32 v126, v64, v65
	v_cvt_pk_bf16_f32 v127, v66, v67
	v_cvt_pk_bf16_f32 v128, v68, v69
	v_cvt_pk_bf16_f32 v129, v70, v71
	v_cvt_pk_bf16_f32 v134, v86, v87
	v_cvt_pk_bf16_f32 v135, v88, v89
	v_cvt_pk_bf16_f32 v136, v90, v91
	v_cvt_pk_bf16_f32 v137, v92, v93
	v_cvt_pk_bf16_f32 v122, v72, v73
	v_cvt_pk_bf16_f32 v123, v74, v75
	v_cvt_pk_bf16_f32 v124, v76, v77
	v_cvt_pk_bf16_f32 v125, v78, v79
	s_mov_b32 s28, s48
	s_andn2_b64 vcc, exec, s[20:21]
	s_cbranch_vccnz .LBB0_375

; template <int KIND>
; DI void attn_unit(const Frame& F, int qrow0, int head, int ctx_row0, int lat_row0, int ntiles) {
;     ...
;     bf16x8 pfa[2][2], pfb[2][2];
;     f32x16 s0, s1, n0, n1;
.LBB0_423:
	v_lshl_add_u64 v[164:165], v[154:155], 0, s[44:45]
	v_add_co_u32_e32 v64, vcc, 0xa300000, v164
	s_add_i32 s4, s27, 0xffffe000
	s_nop 0
	v_addc_co_u32_e32 v65, vcc, 0, v165, vcc
	global_load_dwordx4 v[130:133], v[64:65], off
	s_cmp_lg_u32 s27, 0
	s_cselect_b32 s4, s4, 0x4000
	v_add_u32_e32 v160, s4, v174
	ds_read_b64_tr_b16 v[234:235], v160 offset:28672
	ds_read_b64_tr_b16 v[236:237], v160 offset:29184
	ds_read_b64_tr_b16 v[238:239], v160 offset:32768
	ds_read_b64_tr_b16 v[240:241], v160 offset:33280
	ds_read_b64_tr_b16 v[242:243], v160 offset:29696
	ds_read_b64_tr_b16 v[244:245], v160 offset:30208
	ds_read_b64_tr_b16 v[246:247], v160 offset:33792
	ds_read_b64_tr_b16 v[248:249], v160 offset:34304
	ds_read_b128 v[188:191], v170
	ds_read_b128 v[192:195], v170 offset:32
	ds_read_b128 v[196:199], v170 offset:64
	ds_read_b128 v[200:203], v170 offset:96
	v_xor_b32_e32 v64, 0x80000000, v172
	v_mov_b32_e32 v65, v64
	v_mov_b64_e32 v[66:67], v[64:65]
	v_mov_b64_e32 v[68:69], v[64:65]
	v_mov_b64_e32 v[70:71], v[64:65]
	v_mov_b64_e32 v[72:73], v[64:65]
	v_mov_b64_e32 v[74:75], v[64:65]
	v_mov_b64_e32 v[76:77], v[64:65]
	v_mov_b64_e32 v[78:79], v[64:65]
	v_exp_f32_e32 v34, v34
	v_exp_f32_e32 v35, v35
	s_waitcnt lgkmcnt(10)
	v_mfma_f32_32x32x16_bf16 v[16:31], v[234:237], v[142:145], v[16:31]
	ds_read_b128 v[204:207], v171 offset:9216
	ds_read_b128 v[208:211], v171 offset:9248
	ds_read_b64_tr_b16 v[226:227], v160 offset:31744
	ds_read_b64_tr_b16 v[228:229], v160 offset:32256
	ds_read_b64_tr_b16 v[230:231], v160 offset:35840
	s_waitcnt lgkmcnt(14)
	ds_read_b64_tr_b16 v[232:233], v160 offset:36352
	s_waitcnt lgkmcnt(14)
	v_mfma_f32_32x32x16_bf16 v[0:15], v[238:241], v[142:145], v[0:15]
	v_exp_f32_e32 v142, v48
	v_exp_f32_e32 v48, v32
	v_exp_f32_e32 v143, v49
	s_waitcnt lgkmcnt(12)
	v_mfma_f32_32x32x16_bf16 v[16:31], v[242:245], v[146:149], v[16:31]
	v_exp_f32_e32 v49, v33
	v_exp_f32_e32 v144, v50
	v_exp_f32_e32 v145, v51
	s_waitcnt lgkmcnt(10)
	v_mfma_f32_32x32x16_bf16 v[0:15], v[246:249], v[146:149], v[0:15]
	v_exp_f32_e32 v50, v36
	v_exp_f32_e32 v32, v40
	v_exp_f32_e32 v33, v41
	s_waitcnt lgkmcnt(9)
	v_mfma_f32_32x32x16_bf16 v[80:95], v[188:191], v[98:101], v[64:79]
	ds_read_b128 v[188:191], v170 offset:4640
	v_exp_f32_e32 v40, v46
	v_exp_f32_e32 v41, v47
	v_exp_f32_e32 v51, v37
	s_waitcnt lgkmcnt(9)
	v_mfma_f32_32x32x16_bf16 v[80:95], v[192:195], v[102:105], v[80:95]
	ds_read_b128 v[192:195], v170 offset:4672
	v_exp_f32_e32 v146, v52
	v_exp_f32_e32 v147, v53
	v_exp_f32_e32 v52, v56
	s_waitcnt lgkmcnt(9)
	v_mfma_f32_32x32x16_bf16 v[80:95], v[196:199], v[106:109], v[80:95]
	ds_read_b128 v[196:199], v170 offset:4704
	v_exp_f32_e32 v53, v57
	v_exp_f32_e32 v56, v58
	v_exp_f32_e32 v57, v59
	s_waitcnt lgkmcnt(9)
	v_mfma_f32_32x32x16_bf16 v[80:95], v[200:203], v[110:113], v[80:95]
	ds_read_b128 v[200:203], v171 offset:11776
	v_exp_f32_e32 v148, v54
	v_exp_f32_e32 v54, v38
	v_exp_f32_e32 v149, v55
	s_waitcnt lgkmcnt(9)
	v_mfma_f32_32x32x16_bf16 v[80:95], v[204:207], v[114:117], v[80:95]
	ds_read_b128 v[204:207], v171 offset:11808
	v_exp_f32_e32 v55, v39
	v_exp_f32_e32 v36, v42
	v_exp_f32_e32 v37, v43
	s_waitcnt lgkmcnt(9)
	v_mfma_f32_32x32x16_bf16 v[80:95], v[208:211], v[118:121], v[80:95]
	ds_read_b128 v[208:211], v170 offset:4608
	v_exp_f32_e32 v42, v60
	v_exp_f32_e32 v38, v44
	v_exp_f32_e32 v43, v61
	s_waitcnt lgkmcnt(5)
	v_mfma_f32_32x32x16_bf16 v[64:79], v[188:191], v[102:105], v[64:79]
	v_exp_f32_e32 v39, v45
	v_exp_f32_e32 v44, v62
	v_exp_f32_e32 v45, v63
	s_waitcnt lgkmcnt(4)
	v_mfma_f32_32x32x16_bf16 v[64:79], v[192:195], v[106:109], v[64:79]
	v_add_f32_e32 v46, v34, v35
	v_add_f32_e32 v47, v142, v48
	v_add_f32_e32 v46, v143, v46
	v_add_f32_e32 v47, v49, v47
	v_add_f32_e32 v46, v144, v46
	v_add_f32_e32 v47, v145, v47
	s_waitcnt lgkmcnt(3)
	v_mfma_f32_32x32x16_bf16 v[64:79], v[196:199], v[110:113], v[64:79]
	v_add_f32_e32 v46, v50, v46
	v_add_f32_e32 v47, v32, v47
	v_add_f32_e32 v46, v33, v46
	v_add_f32_e32 v47, v40, v47
	v_add_f32_e32 v46, v41, v46
	v_add_f32_e32 v47, v51, v47
	s_waitcnt lgkmcnt(2)
	v_mfma_f32_32x32x16_bf16 v[64:79], v[200:203], v[114:117], v[64:79]
	v_add_f32_e32 v46, v146, v46
	v_add_f32_e32 v47, v147, v47
	v_add_f32_e32 v46, v52, v46
	v_add_f32_e32 v47, v53, v47
	v_add_f32_e32 v46, v56, v46
	v_add_f32_e32 v47, v57, v47
	s_waitcnt lgkmcnt(1)
	v_mfma_f32_32x32x16_bf16 v[64:79], v[204:207], v[118:121], v[64:79]
	ds_read_b64_tr_b16 v[204:205], v160 offset:30720
	ds_read_b64_tr_b16 v[206:207], v160 offset:31232
	v_add_f32_e32 v46, v148, v46
	v_add_f32_e32 v47, v54, v47
	v_add_f32_e32 v46, v149, v46
	v_add_f32_e32 v47, v55, v47
	v_add_f32_e32 v46, v36, v46
	v_add_f32_e32 v47, v37, v47
	s_waitcnt lgkmcnt(2)
	v_mfma_f32_32x32x16_bf16 v[64:79], v[208:211], v[98:101], v[64:79]
	ds_read_b64_tr_b16 v[208:209], v160 offset:34816
	ds_read_b64_tr_b16 v[210:211], v160 offset:35328
	v_add_f32_e32 v46, v42, v46
	v_add_f32_e32 v47, v38, v47
	v_add_f32_e32 v46, v43, v46
	v_add_f32_e32 v47, v39, v47
	v_add_f32_e32 v46, v44, v46
	v_add_f32_e32 v47, v45, v47
	v_mfma_f32_32x32x16_bf16 v[16:31], v[226:229], v[138:141], v[16:31]
	v_add_f32_e32 v46, v46, v47
	v_mfma_f32_32x32x16_bf16 v[0:15], v[230:233], v[138:141], v[0:15]
	s_waitcnt lgkmcnt(2)
	v_mfma_f32_32x32x16_bf16 v[16:31], v[204:207], v[134:137], v[16:31]
	s_waitcnt lgkmcnt(0)
	v_mfma_f32_32x32x16_bf16 v[0:15], v[208:211], v[134:137], v[0:15]
	v_cmp_lt_f32_e32 vcc, s1, v46
	v_mov_b32_e32 v160, v46
	s_cbranch_vccnz .LBB0_445
	v_cvt_pk_bf16_f32 v142, v142, v143
	v_cvt_pk_bf16_f32 v143, v144, v145
	v_cvt_pk_bf16_f32 v144, v146, v147
	v_cvt_pk_bf16_f32 v145, v148, v149
	v_cvt_pk_bf16_f32 v134, v48, v49
	v_cvt_pk_bf16_f32 v135, v34, v35
	v_cvt_pk_bf16_f32 v136, v50, v51
	v_cvt_pk_bf16_f32 v137, v54, v55
	v_cvt_pk_bf16_f32 v146, v52, v53
	v_cvt_pk_bf16_f32 v147, v56, v57
	v_cvt_pk_bf16_f32 v148, v42, v43
	v_cvt_pk_bf16_f32 v149, v44, v45
	v_cvt_pk_bf16_f32 v138, v32, v33
	v_cvt_pk_bf16_f32 v139, v36, v37
	v_cvt_pk_bf16_f32 v140, v38, v39
	v_cvt_pk_bf16_f32 v141, v40, v41
	v_cndmask_b32_e64 v32, 0, 1, s[20:21]
	v_cmp_ne_u32_e64 s[4:5], 1, v32
	s_andn2_b64 vcc, exec, s[20:21]
	s_cbranch_vccnz .LBB0_428

; template <int KIND>
; DI void attn_unit(const Frame& F, int qrow0, int head, int ctx_row0, int lat_row0, int ntiles) {
;     ...
;     bf16x8 pfa[2][2], pfb[2][2];
;     f32x16 s0, s1, n0, n1;
.LBB0_434:
	s_add_i32 s4, s27, 0xffffe000
	s_cmp_lg_u32 s27, 0
	s_cselect_b32 s4, s4, 0x4000
	ds_read_b128 v[162:165], v170 offset:14336
	ds_read_b128 v[188:191], v170 offset:14368
	ds_read_b128 v[192:195], v170 offset:14400
	ds_read_b128 v[196:199], v170 offset:14432
	ds_read_b128 v[200:203], v171 offset:23552
	ds_read_b128 v[204:207], v171 offset:23584
	v_xor_b32_e32 v32, 0x80000000, v172
	v_mov_b32_e32 v33, v32
	v_mov_b64_e32 v[34:35], v[32:33]
	v_mov_b64_e32 v[36:37], v[32:33]
	v_mov_b64_e32 v[38:39], v[32:33]
	v_mov_b64_e32 v[40:41], v[32:33]
	v_mov_b64_e32 v[42:43], v[32:33]
	v_mov_b64_e32 v[44:45], v[32:33]
	v_mov_b64_e32 v[46:47], v[32:33]
	v_pk_add_f32 v[160:161], v[160:161], v[160:161] op_sel:[0,1] op_sel_hi:[1,0]
	v_add_u32_e32 v161, s4, v174
	ds_read_b64_tr_b16 v[234:235], v161 offset:28672
	ds_read_b64_tr_b16 v[236:237], v161 offset:29184
	ds_read_b64_tr_b16 v[238:239], v161 offset:32768
	ds_read_b64_tr_b16 v[240:241], v161 offset:33280
	ds_read_b64_tr_b16 v[242:243], v161 offset:29696
	ds_read_b64_tr_b16 v[244:245], v161 offset:30208
	s_waitcnt lgkmcnt(11)
	v_mfma_f32_32x32x16_bf16 v[48:63], v[162:165], v[98:101], v[32:47]
	ds_read_b64_tr_b16 v[246:247], v161 offset:33792
	ds_read_b64_tr_b16 v[248:249], v161 offset:34304
	ds_read_b128 v[162:165], v170 offset:18976
	ds_read_b64_tr_b16 v[208:209], v161 offset:31744
	s_waitcnt lgkmcnt(14)
	ds_read_b64_tr_b16 v[210:211], v161 offset:32256
	s_waitcnt lgkmcnt(14)
	ds_read_b64_tr_b16 v[226:227], v161 offset:35840
	v_mfma_f32_32x32x16_bf16 v[48:63], v[188:191], v[102:105], v[48:63]
	v_mfma_f32_32x32x16_bf16 v[48:63], v[192:195], v[106:109], v[48:63]
	s_waitcnt lgkmcnt(14)
	v_mfma_f32_32x32x16_bf16 v[48:63], v[196:199], v[110:113], v[48:63]
	s_waitcnt lgkmcnt(13)
	v_mfma_f32_32x32x16_bf16 v[48:63], v[200:203], v[114:117], v[48:63]
	s_waitcnt lgkmcnt(12)
	v_mfma_f32_32x32x16_bf16 v[48:63], v[204:207], v[118:121], v[48:63]
	ds_read_b128 v[188:191], v170 offset:19008
	ds_read_b128 v[192:195], v170 offset:19040
	ds_read_b128 v[196:199], v171 offset:26112
	s_waitcnt lgkmcnt(14)
	ds_read_b128 v[200:203], v171 offset:26144
	s_waitcnt lgkmcnt(14)
	ds_read_b128 v[204:207], v170 offset:18944
	s_waitcnt lgkmcnt(14)
	ds_read_b64_tr_b16 v[228:229], v161 offset:36352
	v_mfma_f32_32x32x16_bf16 v[16:31], v[234:237], v[142:145], v[16:31]
	s_waitcnt lgkmcnt(14)
	v_mfma_f32_32x32x16_bf16 v[0:15], v[238:241], v[142:145], v[0:15]
	v_exp_f32_e32 v142, v80
	v_exp_f32_e32 v80, v64
	v_exp_f32_e32 v143, v81
	s_waitcnt lgkmcnt(12)
	v_mfma_f32_32x32x16_bf16 v[16:31], v[242:245], v[146:149], v[16:31]
	v_exp_f32_e32 v81, v65
	v_exp_f32_e32 v144, v82
	v_exp_f32_e32 v82, v66
	s_waitcnt lgkmcnt(10)
	v_mfma_f32_32x32x16_bf16 v[0:15], v[246:249], v[146:149], v[0:15]
	v_exp_f32_e32 v145, v83
	v_exp_f32_e32 v83, v67
	v_exp_f32_e32 v64, v72
	s_waitcnt lgkmcnt(9)
	v_mfma_f32_32x32x16_bf16 v[32:47], v[162:165], v[102:105], v[32:47]
	v_exp_f32_e32 v65, v73
	v_exp_f32_e32 v72, v78
	v_exp_f32_e32 v73, v79
	s_waitcnt lgkmcnt(5)
	v_mfma_f32_32x32x16_bf16 v[32:47], v[188:191], v[106:109], v[32:47]
	v_exp_f32_e32 v146, v84
	v_exp_f32_e32 v84, v68
	v_exp_f32_e32 v147, v85
	s_waitcnt lgkmcnt(4)
	v_mfma_f32_32x32x16_bf16 v[32:47], v[192:195], v[110:113], v[32:47]
	v_exp_f32_e32 v85, v69
	v_exp_f32_e32 v148, v86
	v_exp_f32_e32 v86, v70
	s_waitcnt lgkmcnt(3)
	v_mfma_f32_32x32x16_bf16 v[32:47], v[196:199], v[114:117], v[32:47]
	v_exp_f32_e32 v149, v87
	v_exp_f32_e32 v87, v71
	v_exp_f32_e32 v70, v88
	s_waitcnt lgkmcnt(2)
	v_mfma_f32_32x32x16_bf16 v[32:47], v[200:203], v[118:121], v[32:47]
	ds_read_b64_tr_b16 v[200:201], v161 offset:30720
	ds_read_b64_tr_b16 v[202:203], v161 offset:31232
	v_exp_f32_e32 v71, v89
	v_exp_f32_e32 v88, v90
	v_exp_f32_e32 v89, v91
	s_waitcnt lgkmcnt(3)
	v_mfma_f32_32x32x16_bf16 v[32:47], v[204:207], v[98:101], v[32:47]
	ds_read_b64_tr_b16 v[204:205], v161 offset:34816
	ds_read_b64_tr_b16 v[206:207], v161 offset:35328
	v_exp_f32_e32 v66, v74
	v_exp_f32_e32 v67, v75
	v_exp_f32_e32 v74, v92
	v_mfma_f32_32x32x16_bf16 v[16:31], v[208:211], v[138:141], v[16:31]
	v_exp_f32_e32 v68, v76
	v_exp_f32_e32 v75, v93
	v_exp_f32_e32 v69, v77
	s_waitcnt lgkmcnt(4)
	v_mfma_f32_32x32x16_bf16 v[0:15], v[226:229], v[138:141], v[0:15]
	v_exp_f32_e32 v76, v94
	v_exp_f32_e32 v77, v95
	v_add_f32_e32 v78, v142, v80
	v_add_f32_e32 v79, v143, v81
	v_add_f32_e32 v78, v144, v78
	v_add_f32_e32 v79, v82, v79
	s_waitcnt lgkmcnt(2)
	v_mfma_f32_32x32x16_bf16 v[16:31], v[200:203], v[134:137], v[16:31]
	v_add_f32_e32 v78, v145, v78
	v_add_f32_e32 v79, v83, v79
	v_add_f32_e32 v78, v64, v78
	v_add_f32_e32 v79, v65, v79
	v_add_f32_e32 v78, v72, v78
	v_add_f32_e32 v79, v73, v79
	v_add_f32_e32 v78, v146, v78
	v_add_f32_e32 v79, v84, v79
	s_waitcnt lgkmcnt(0)
	v_mfma_f32_32x32x16_bf16 v[0:15], v[204:207], v[134:137], v[0:15]
	v_add_f32_e32 v78, v147, v78
	v_add_f32_e32 v79, v85, v79
	v_add_f32_e32 v78, v148, v78
	v_add_f32_e32 v79, v86, v79
	v_add_f32_e32 v78, v149, v78
	v_add_f32_e32 v79, v87, v79
	v_add_f32_e32 v78, v70, v78
	v_add_f32_e32 v79, v71, v79
	v_add_f32_e32 v78, v88, v78
	v_add_f32_e32 v79, v89, v79
	v_add_f32_e32 v78, v66, v78
	v_add_f32_e32 v79, v67, v79
	v_add_f32_e32 v78, v74, v78
	v_add_f32_e32 v79, v68, v79
	v_add_f32_e32 v78, v75, v78
	v_add_f32_e32 v79, v69, v79
	v_add_f32_e32 v78, v76, v78
	v_add_f32_e32 v79, v77, v79
	v_add_f32_e32 v78, v78, v79
	v_cmp_lt_f32_e32 vcc, s1, v78
	s_cbranch_vccnz .LBB0_446
	v_cvt_pk_bf16_f32 v142, v142, v143
	v_cvt_pk_bf16_f32 v143, v144, v145
	v_cvt_pk_bf16_f32 v144, v146, v147
	v_cvt_pk_bf16_f32 v145, v148, v149
	v_cvt_pk_bf16_f32 v134, v80, v81
	v_cvt_pk_bf16_f32 v135, v82, v83
	v_cvt_pk_bf16_f32 v136, v84, v85
	v_cvt_pk_bf16_f32 v137, v86, v87
	v_cvt_pk_bf16_f32 v146, v70, v71
	v_cvt_pk_bf16_f32 v147, v88, v89
	v_cvt_pk_bf16_f32 v148, v74, v75
	v_cvt_pk_bf16_f32 v149, v76, v77
	v_cvt_pk_bf16_f32 v138, v64, v65
	v_cvt_pk_bf16_f32 v139, v66, v67
	v_cvt_pk_bf16_f32 v140, v68, v69
	v_cvt_pk_bf16_f32 v141, v72, v73
	s_andn2_b64 vcc, exec, s[20:21]
	s_cbranch_vccnz .LBB0_439

; #define LAS __attribute__((address_space(3)))
; DI void conv_item(const float* W, int K, int ld, int kind, const float* gain, bf16_t* WT, int item, int nblk, LAS float* scr, int lane) {
;     const int kb = item / nblk, nb = item % nblk, k0 = 64 * kb, n0 = 32 * nb;
;     const int sc_ = srcmap(kind, n0 + (lane & 31));
;     float wv[32];
; #pragma unroll
;     for (int i = 0; i < 32; ++i) wv[i] = W[(size_t)(k0 + 2 * i + (lane >> 5)) * ld + sc_];
; DI void phase_att(const Frame& F) {
;     ...
;     if (F.bid < 128) {
;         __syncthreads();
;         const int cr = (F.bid & 7) * 16 + (F.bid >> 3);
;         convert_weights<5, 11>(F, F.l, cr, 128);
.LBB0_491:
	s_cmpk_lt_u32 s96, 0x80
	s_cbranch_scc1 .LBB0_506
	v_readlane_b32 s4, v255, 31
	s_lshl_b32 s3, s4, 14
	s_and_b32 s10, s96, 0x7f
	s_lshl_b32 s2, s10, 7
	s_add_i32 s16, s3, 0
	s_mov_b32 s3, s10
	s_or_b32 s10, s2, s3
	s_and_b32 s2, s10, 0x3f8
	s_add_i32 s18, s4, s2
	s_lshl_b64 s[2:3], s[44:45], 3
	s_add_u32 s8, s62, s2
	s_addc_u32 s9, s63, s3
	s_waitcnt vmcnt(0) lgkmcnt(0)
	s_barrier
	s_load_dwordx4 s[12:15], s[8:9], 0x80
	s_load_dwordx2 s[2:3], s[8:9], 0x90
	s_load_dwordx4 s[4:7], s[8:9], 0xa8
	v_readlane_b32 s11, v255, 35
	s_lshl_b32 s19, s11, 19
	s_and_b32 s20, s18, 0x3ff
	s_cmpk_lt_u32 s20, 0x100
	s_cbranch_scc0 .LBB0_498
	s_load_dwordx2 s[8:9], s[8:9], 0x78
	s_lshl_b32 s11, s19, 2
	v_and_b32_e32 v4, 31, v225
	v_lshrrev_b32_e32 v5, 5, v186
	v_mov_b32_e32 v1, v97
	s_waitcnt lgkmcnt(0)
	s_add_u32 s22, s8, s11
	s_addc_u32 s23, s9, 0
	s_lshl_b32 s8, s18, 1
	s_and_b32 s9, s8, 0x1c0
	s_lshl_b32 s8, s18, 5
	s_and_b32 s8, s8, 0x3e0
	v_or_b32_e32 v0, s8, v4
	v_lshlrev_b32_e32 v0, 2, v0
	v_or_b32_e32 v2, s9, v5
	v_lshl_add_u64 v[0:1], s[22:23], 0, v[0:1]
	v_lshlrev_b32_e32 v2, 12, v2
	v_mov_b32_e32 v3, v97
	v_lshl_add_u64 v[0:1], v[0:1], 0, v[2:3]
	s_mov_b32 s11, 0x3e000
	v_add_co_u32_e32 v2, vcc, s11, v0
	s_mov_b32 s11, 0x3a000
	s_nop 0
	v_addc_co_u32_e32 v3, vcc, 0, v1, vcc
	global_load_dword v6, v[2:3], off
	v_add_co_u32_e32 v2, vcc, s0, v0
	s_lshl_b32 s9, s9, 1
	s_nop 0
	v_addc_co_u32_e32 v3, vcc, 0, v1, vcc
	global_load_dword v7, v[2:3], off
	v_add_co_u32_e32 v2, vcc, s11, v0
	s_mov_b32 s11, 0x38000
	s_nop 0
	v_addc_co_u32_e32 v3, vcc, 0, v1, vcc
	global_load_dword v8, v[2:3], off
	v_add_co_u32_e32 v2, vcc, s11, v0
	s_mov_b32 s11, 0x34000
	s_nop 0
	v_addc_co_u32_e32 v3, vcc, 0, v1, vcc
	global_load_dword v9, v[2:3], off
	v_add_co_u32_e32 v2, vcc, s90, v0
	s_add_u32 s22, s94, s9
	s_nop 0
	v_addc_co_u32_e32 v3, vcc, 0, v1, vcc
	global_load_dword v10, v[2:3], off
	v_add_co_u32_e32 v2, vcc, s11, v0
	s_mov_b32 s11, 0x32000
	s_nop 0
	v_addc_co_u32_e32 v3, vcc, 0, v1, vcc
	global_load_dword v11, v[2:3], off
	v_add_co_u32_e32 v2, vcc, s11, v0
	s_mov_b32 s11, 0x30000
	s_nop 0
	v_addc_co_u32_e32 v3, vcc, 0, v1, vcc
	global_load_dword v12, v[2:3], off
	v_add_co_u32_e32 v2, vcc, s11, v0
	s_mov_b32 s11, 0x2e000
	s_nop 0
	v_addc_co_u32_e32 v3, vcc, 0, v1, vcc
	global_load_dword v13, v[2:3], off
	v_add_co_u32_e32 v2, vcc, s11, v0
	s_mov_b32 s11, 0x2c000
	s_nop 0
	v_addc_co_u32_e32 v3, vcc, 0, v1, vcc
	global_load_dword v14, v[2:3], off
	v_add_co_u32_e32 v2, vcc, s11, v0
	s_mov_b32 s11, 0x2a000
	s_nop 0
	v_addc_co_u32_e32 v3, vcc, 0, v1, vcc
	global_load_dword v15, v[2:3], off
	v_add_co_u32_e32 v2, vcc, s11, v0
	s_mov_b32 s11, 0x28000
	s_nop 0
	v_addc_co_u32_e32 v3, vcc, 0, v1, vcc
	global_load_dword v16, v[2:3], off
	v_add_co_u32_e32 v2, vcc, s11, v0
	s_mov_b32 s11, 0x24000
	s_nop 0
	v_addc_co_u32_e32 v3, vcc, 0, v1, vcc
	global_load_dword v17, v[2:3], off
	v_add_co_u32_e32 v2, vcc, s31, v0
	s_addc_u32 s23, s95, 0
	s_nop 0
	v_addc_co_u32_e32 v3, vcc, 0, v1, vcc
	global_load_dword v18, v[2:3], off
	v_add_co_u32_e32 v2, vcc, s11, v0
	s_mov_b32 s11, 0x22000
	s_nop 0
	v_addc_co_u32_e32 v3, vcc, 0, v1, vcc
	global_load_dword v19, v[2:3], off
	v_add_co_u32_e32 v2, vcc, s11, v0
	s_mov_b32 s11, 0x20000
	s_nop 0
	v_addc_co_u32_e32 v3, vcc, 0, v1, vcc
	global_load_dword v20, v[2:3], off
	v_add_co_u32_e32 v2, vcc, s11, v0
	s_mov_b32 s11, 0x1e000
	s_nop 0
	v_addc_co_u32_e32 v3, vcc, 0, v1, vcc
	global_load_dword v21, v[2:3], off
	v_add_co_u32_e32 v2, vcc, s11, v0
	s_mov_b32 s11, 0x1a000
	s_nop 0
	v_addc_co_u32_e32 v3, vcc, 0, v1, vcc
	global_load_dword v22, v[2:3], off
	v_add_co_u32_e32 v2, vcc, s50, v0
	s_nop 1
	v_addc_co_u32_e32 v3, vcc, 0, v1, vcc
	global_load_dword v23, v[2:3], off
	v_add_co_u32_e32 v2, vcc, s11, v0
	s_mov_b32 s11, 0x18000
	s_nop 0
	v_addc_co_u32_e32 v3, vcc, 0, v1, vcc
	global_load_dword v24, v[2:3], off
	v_add_co_u32_e32 v2, vcc, s11, v0
	s_mov_b32 s11, 0x16000
	s_nop 0
	v_addc_co_u32_e32 v3, vcc, 0, v1, vcc
	global_load_dword v25, v[2:3], off
	v_add_co_u32_e32 v2, vcc, s11, v0
	s_mov_b32 s11, 0x14000
	s_nop 0
	v_addc_co_u32_e32 v3, vcc, 0, v1, vcc
	global_load_dword v26, v[2:3], off
	v_add_co_u32_e32 v2, vcc, s11, v0
	s_mov_b32 s11, 0x10000
	s_nop 0
	v_addc_co_u32_e32 v3, vcc, 0, v1, vcc
	global_load_dword v27, v[2:3], off
	v_add_co_u32_e32 v2, vcc, s89, v0
	s_nop 1
	v_addc_co_u32_e32 v3, vcc, 0, v1, vcc
	global_load_dword v28, v[2:3], off
	v_add_co_u32_e32 v2, vcc, s11, v0
	s_mov_b32 s11, 0xe000
	s_nop 0
	v_addc_co_u32_e32 v3, vcc, 0, v1, vcc
	global_load_dword v29, v[2:3], off
	v_add_co_u32_e32 v2, vcc, s11, v0
	s_mov_b32 s11, 0xc000
	s_nop 0
	v_addc_co_u32_e32 v3, vcc, 0, v1, vcc
	global_load_dword v30, v[2:3], off
	v_add_co_u32_e32 v2, vcc, s11, v0
	s_mov_b32 s11, 0xa000
	s_nop 0
	v_addc_co_u32_e32 v3, vcc, 0, v1, vcc
	global_load_dword v31, v[2:3], off
	v_add_co_u32_e32 v2, vcc, s11, v0
	s_mov_b32 s11, 0x8000
	s_nop 0
	v_addc_co_u32_e32 v3, vcc, 0, v1, vcc
	global_load_dword v32, v[2:3], off
	v_add_co_u32_e32 v2, vcc, s11, v0
	s_movk_i32 s11, 0x6000
	s_nop 0
	v_addc_co_u32_e32 v3, vcc, 0, v1, vcc
	global_load_dword v33, v[2:3], off
	v_add_co_u32_e32 v2, vcc, s11, v0
	s_movk_i32 s11, 0x4000
	s_nop 0
	v_addc_co_u32_e32 v3, vcc, 0, v1, vcc
	global_load_dword v34, v[2:3], off
	v_add_co_u32_e32 v2, vcc, s11, v0
	s_nop 1
	v_addc_co_u32_e32 v3, vcc, 0, v1, vcc
	global_load_dword v35, v[2:3], off
	v_add_co_u32_e32 v2, vcc, s54, v0
	s_nop 1
	v_addc_co_u32_e32 v3, vcc, 0, v1, vcc
	global_load_dword v2, v[2:3], off
	s_nop 0
	global_load_dword v0, v[0:1], off
	v_lshlrev_b32_e32 v1, 2, v4
	v_mul_u32_u24_e32 v3, 0x84, v5
	v_add3_u32 v1, s16, v1, v3
	s_waitcnt vmcnt(0)
; #define LAS __attribute__((address_space(3)))
; DI unsigned pk2(float lo, float hi) { f32x2 v = {lo, hi}; bf16x2_t b = __builtin_convertvector(v, bf16x2_t); return __builtin_bit_cast(unsigned, b); }
; DI void conv_item(const float* W, int K, int ld, int kind, const float* gain, bf16_t* WT, int item, int nblk, LAS float* scr, int lane) {
;     ...
;     for (int i = 0; i < 32; ++i) scr[(2 * i + (lane >> 5)) * 33 + (lane & 31)] = wv[i];
;     asm volatile("s_waitcnt lgkmcnt(0)" ::: "memory");
;     const int c = lane & 7;
; #pragma unroll
;     for (int j = 0; j < 4; ++j) { const int n = (lane >> 3) + 8 * j; const LAS float* s = scr + (8 * c) * 33 + n;
;         u32x4 o; o.x = pk2(s[0 * 33], s[1 * 33]); o.y = pk2(s[2 * 33], s[3 * 33]); o.z = pk2(s[4 * 33], s[5 * 33]); o.w = pk2(s[6 * 33], s[7 * 33]);
;         *(u32x4*)(WT + (size_t)(n0 + n) * K + k0 + 8 * c) = o; }
;     asm volatile("s_waitcnt lgkmcnt(0)" ::: "memory");
	ds_write2_b32 v1, v0, v2 offset1:66
	ds_write2_b32 v1, v35, v34 offset0:132 offset1:198
	v_add_u32_e32 v0, 0x400, v1
	ds_write2_b32 v0, v33, v32 offset0:8 offset1:74
	ds_write2_b32 v0, v31, v30 offset0:140 offset1:206
	v_add_u32_e32 v0, 0x800, v1
	ds_write2_b32 v0, v29, v28 offset0:16 offset1:82
	ds_write2_b32 v0, v27, v26 offset0:148 offset1:214
	v_add_u32_e32 v0, 0xc00, v1
	ds_write2_b32 v0, v25, v24 offset0:24 offset1:90
	ds_write2_b32 v0, v23, v22 offset0:156 offset1:222
	v_add_u32_e32 v0, 0x1000, v1
	ds_write2_b32 v0, v21, v20 offset0:32 offset1:98
	ds_write2_b32 v0, v19, v18 offset0:164 offset1:230
	v_add_u32_e32 v0, 0x1400, v1
	ds_write2_b32 v0, v17, v16 offset0:40 offset1:106
	ds_write2_b32 v0, v15, v14 offset0:172 offset1:238
	v_add_u32_e32 v0, 0x1800, v1
	ds_write2_b32 v0, v13, v12 offset0:48 offset1:114
	ds_write2_b32 v0, v11, v10 offset0:180 offset1:246
	v_add_u32_e32 v0, 0x1c00, v1
	ds_write2_b32 v0, v9, v8 offset0:56 offset1:122
	ds_write2_b32 v0, v7, v6 offset0:188 offset1:254
	v_lshlrev_b32_e32 v0, 3, v186
	v_and_b32_e32 v0, 56, v0
	v_mul_u32_u24_e32 v2, 0x84, v0
	v_lshlrev_b32_e32 v0, 1, v0
	v_mov_b32_e32 v1, v97
	v_lshrrev_b32_e32 v22, 3, v186
	v_lshl_add_u64 v[0:1], s[22:23], 0, v[0:1]
	s_mov_b64 s[22:23], 0x2100000
	v_lshl_add_u64 v[4:5], v[0:1], 0, s[22:23]
	v_lshlrev_b32_e32 v0, 2, v22
	s_waitcnt lgkmcnt(0)
	v_add3_u32 v26, s16, v2, v0
	ds_read2_b32 v[6:7], v26 offset0:33 offset1:41
	ds_read2_b32 v[8:9], v26 offset1:8
	ds_read2_b32 v[10:11], v26 offset0:66 offset1:74
	ds_read2_b32 v[12:13], v26 offset0:99 offset1:107
	ds_read2_b32 v[14:15], v26 offset0:132 offset1:140
	ds_read2_b32 v[16:17], v26 offset0:165 offset1:173
	ds_read2_b32 v[18:19], v26 offset0:198 offset1:206
	ds_read2_b32 v[20:21], v26 offset0:231 offset1:239
	v_mov_b32_e32 v23, v97
	s_waitcnt lgkmcnt(6)
	v_cvt_pk_bf16_f32 v0, v8, v6
	v_or_b32_e32 v6, s8, v22
	v_lshlrev_b32_e32 v22, 10, v6
	s_waitcnt lgkmcnt(4)
	v_cvt_pk_bf16_f32 v1, v10, v12
	s_waitcnt lgkmcnt(2)
	v_cvt_pk_bf16_f32 v2, v14, v16
	s_waitcnt lgkmcnt(0)
	v_cvt_pk_bf16_f32 v3, v18, v20
	v_lshl_add_u64 v[24:25], v[4:5], 0, v[22:23]
	global_store_dwordx4 v[24:25], v[0:3], off
	v_or_b32_e32 v6, 0x2000, v22
	v_or_b32_e32 v24, 0x4000, v22
	v_cvt_pk_bf16_f32 v0, v9, v7
	v_mov_b32_e32 v7, v97
	v_cvt_pk_bf16_f32 v1, v11, v13
	v_cvt_pk_bf16_f32 v2, v15, v17
	v_cvt_pk_bf16_f32 v3, v19, v21
	v_lshl_add_u64 v[6:7], v[4:5], 0, v[6:7]
	global_store_dwordx4 v[6:7], v[0:3], off
	ds_read2_b32 v[6:7], v26 offset0:49 offset1:57
	ds_read2_b32 v[8:9], v26 offset0:16 offset1:24
	ds_read2_b32 v[10:11], v26 offset0:82 offset1:90
	ds_read2_b32 v[12:13], v26 offset0:115 offset1:123
	ds_read2_b32 v[14:15], v26 offset0:148 offset1:156
	ds_read2_b32 v[16:17], v26 offset0:181 offset1:189
	ds_read2_b32 v[18:19], v26 offset0:214 offset1:222
	ds_read2_b32 v[20:21], v26 offset0:247 offset1:255
	v_mov_b32_e32 v25, v97
	s_waitcnt lgkmcnt(6)
	v_cvt_pk_bf16_f32 v0, v8, v6
	s_waitcnt lgkmcnt(4)
	v_cvt_pk_bf16_f32 v1, v10, v12
	s_waitcnt lgkmcnt(2)
	v_cvt_pk_bf16_f32 v2, v14, v16
	s_waitcnt lgkmcnt(0)
	v_cvt_pk_bf16_f32 v3, v18, v20
	v_lshl_add_u64 v[24:25], v[4:5], 0, v[24:25]
	global_store_dwordx4 v[24:25], v[0:3], off
	v_or_b32_e32 v6, 0x6000, v22
	s_nop 0
	v_cvt_pk_bf16_f32 v0, v9, v7
	v_mov_b32_e32 v7, v97
	v_cvt_pk_bf16_f32 v1, v11, v13
	v_cvt_pk_bf16_f32 v2, v15, v17
	v_cvt_pk_bf16_f32 v3, v19, v21
	v_lshl_add_u64 v[4:5], v[4:5], 0, v[6:7]
	global_store_dwordx4 v[4:5], v[0:3], off
	s_waitcnt lgkmcnt(0)
	s_add_i32 s8, s18, 0x300
	s_and_b32 s11, s8, 0x3ff
	s_cmpk_gt_u32 s11, 0xff
	s_cbranch_scc0 .LBB0_499

; template <int ONLY>
; __global__ void __launch_bounds__(512, 2) fwd_kernel(Params prm) {
	.amdhsa_kernel _Z10fwd_kernelILin1EEv6Params
		.amdhsa_group_segment_fixed_size 0
		.amdhsa_private_segment_fixed_size 0
		.amdhsa_kernarg_size 480
		.amdhsa_user_sgpr_count 2
		.amdhsa_user_sgpr_dispatch_ptr 0
		.amdhsa_user_sgpr_queue_ptr 0
		.amdhsa_user_sgpr_kernarg_segment_ptr 1
		.amdhsa_user_sgpr_dispatch_id 0
		.amdhsa_user_sgpr_kernarg_preload_length 0
		.amdhsa_user_sgpr_kernarg_preload_offset 0
		.amdhsa_user_sgpr_private_segment_size 0
		.amdhsa_uses_dynamic_stack 0
		.amdhsa_enable_private_segment 0
		.amdhsa_system_sgpr_workgroup_id_x 1
		.amdhsa_system_sgpr_workgroup_id_y 0
		.amdhsa_system_sgpr_workgroup_id_z 0
		.amdhsa_system_sgpr_workgroup_info 0
		.amdhsa_system_vgpr_workitem_id 2
		.amdhsa_next_free_vgpr 256
		.amdhsa_next_free_sgpr 102
		.amdhsa_accum_offset 256
		.amdhsa_reserve_vcc 1
		.amdhsa_float_round_mode_32 0
		.amdhsa_float_round_mode_16_64 0
		.amdhsa_float_denorm_mode_32 3
		.amdhsa_float_denorm_mode_16_64 3
		.amdhsa_dx10_clamp 1
		.amdhsa_ieee_mode 1
		.amdhsa_fp16_overflow 0
		.amdhsa_tg_split 0
		.amdhsa_exception_fp_ieee_invalid_op 0
		.amdhsa_exception_fp_denorm_src 0
		.amdhsa_exception_fp_ieee_div_zero 0
		.amdhsa_exception_fp_ieee_overflow 0
		.amdhsa_exception_fp_ieee_underflow 0
		.amdhsa_exception_fp_ieee_inexact 0
		.amdhsa_exception_int_div_zero 0
	.end_amdhsa_kernel

; template <int ONLY>
; __global__ void __launch_bounds__(512, 2) fwd_kernel(Params prm) {
amdhsa.kernels:
  - .agpr_count:     0
    .args:
      - .offset:         0
        .size:           224
        .value_kind:     by_value
      - .offset:         224
        .size:           4
        .value_kind:     hidden_block_count_x
      - .offset:         228
        .size:           4
        .value_kind:     hidden_block_count_y
      - .offset:         232
        .size:           4
        .value_kind:     hidden_block_count_z
      - .offset:         236
        .size:           2
        .value_kind:     hidden_group_size_x
      - .offset:         238
        .size:           2
        .value_kind:     hidden_group_size_y
      - .offset:         240
        .size:           2
        .value_kind:     hidden_group_size_z
      - .offset:         242
        .size:           2
        .value_kind:     hidden_remainder_x
      - .offset:         244
        .size:           2
        .value_kind:     hidden_remainder_y
      - .offset:         246
        .size:           2
        .value_kind:     hidden_remainder_z
      - .offset:         264
        .size:           8
        .value_kind:     hidden_global_offset_x
      - .offset:         272
        .size:           8
        .value_kind:     hidden_global_offset_y
      - .offset:         280
        .size:           8
        .value_kind:     hidden_global_offset_z
      - .offset:         288
        .size:           2
        .value_kind:     hidden_grid_dims
      - .offset:         312
        .size:           8
        .value_kind:     hidden_multigrid_sync_arg
      - .offset:         344
        .size:           4
        .value_kind:     hidden_dynamic_lds_size
    .group_segment_fixed_size: 0
    .kernarg_segment_align: 8
    .kernarg_segment_size: 480
    .language:       OpenCL C
    .language_version:
      - 2
      - 0
    .max_flat_workgroup_size: 512
    .name:           _Z10fwd_kernelILin1EEv6Params
    .private_segment_fixed_size: 0
    .sgpr_count:     108
    .sgpr_spill_count: 90
    .symbol:         _Z10fwd_kernelILin1EEv6Params.kd
    .uniform_work_group_size: 1
    .uses_dynamic_stack: false
    .vgpr_count:     256
    .vgpr_spill_count: 0
    .wavefront_size: 64
